# attention steady-state loop: row-max canonicalising self-max instructions removed (MFMA-result wait kept by a longer s_nop)
# speedup vs baseline: 1.0021x; 1.0018x over previous
.LBB0_783:
	v_add_u32_e32 v0, s20, v230
	ds_read_b64_tr_b16 v[192:193], v0 offset:24576
	ds_read_b64_tr_b16 v[194:195], v0 offset:25088
	s_waitcnt lgkmcnt(9)
	v_mfma_f32_32x32x16_bf16 v[112:127], v[188:191], v[148:151], v[48:63]
	v_add_f32_e32 v2, v80, v81
	v_add_f32_e32 v2, v82, v2
	v_add_f32_e32 v2, v83, v2
	v_add_f32_e32 v2, v84, v2
	v_add_f32_e32 v2, v85, v2
	v_cvt_pk_bf16_f32 v156, v80, v81
	v_cvt_pk_bf16_f32 v157, v82, v83
	ds_read_b64_tr_b16 v[80:81], v0 offset:28672
	ds_read_b64_tr_b16 v[82:83], v0 offset:29184
	s_waitcnt lgkmcnt(10)
	v_mfma_f32_32x32x16_bf16 v[96:111], v[184:187], v[148:151], v[48:63]
	v_add_f32_e32 v2, v86, v2
	v_add_f32_e32 v2, v87, v2
	v_add_f32_e32 v2, v88, v2
	v_add_f32_e32 v6, v89, v2
	v_cvt_pk_bf16_f32 v158, v84, v85
	v_cvt_pk_bf16_f32 v159, v86, v87
	ds_read_b64_tr_b16 v[2:3], v0 offset:25600
	ds_read_b64_tr_b16 v[4:5], v0 offset:26112
	s_waitcnt lgkmcnt(11)
	v_mfma_f32_32x32x16_bf16 v[112:127], v[180:183], v[136:139], v[112:127]
	v_add_f32_e32 v6, v90, v6
	v_add_f32_e32 v6, v91, v6
	v_add_f32_e32 v6, v92, v6
	v_add_f32_e32 v10, v93, v6
	v_cvt_pk_bf16_f32 v152, v88, v89
	v_cvt_pk_bf16_f32 v153, v90, v91
	ds_read_b64_tr_b16 v[6:7], v0 offset:29696
	ds_read_b64_tr_b16 v[8:9], v0 offset:30208
	s_waitcnt lgkmcnt(12)
	v_mfma_f32_32x32x16_bf16 v[96:111], v[176:179], v[136:139], v[96:111]
	v_add_f32_e32 v10, v94, v10
	v_add_f32_e32 v10, v95, v10
	v_add_f32_e32 v10, v64, v10
	v_add_f32_e32 v14, v65, v10
	v_cvt_pk_bf16_f32 v154, v92, v93
	v_cvt_pk_bf16_f32 v155, v94, v95
	ds_read_b64_tr_b16 v[10:11], v0 offset:26624
	ds_read_b64_tr_b16 v[12:13], v0 offset:27136
	s_waitcnt lgkmcnt(13)
	v_mfma_f32_32x32x16_bf16 v[112:127], v[172:175], v[132:135], v[112:127]
	v_add_f32_e32 v14, v66, v14
	v_add_f32_e32 v14, v67, v14
	v_add_f32_e32 v14, v68, v14
	v_add_f32_e32 v14, v69, v14
	v_cvt_pk_bf16_f32 v144, v64, v65
	v_cvt_pk_bf16_f32 v145, v66, v67
	ds_read_b64_tr_b16 v[64:65], v0 offset:30720
	ds_read_b64_tr_b16 v[66:67], v0 offset:31232
	s_waitcnt lgkmcnt(14)
	v_mfma_f32_32x32x16_bf16 v[96:111], v[168:171], v[132:135], v[96:111]
	v_add_f32_e32 v14, v70, v14
	v_add_f32_e32 v14, v71, v14
	v_add_f32_e32 v14, v72, v14
	v_add_f32_e32 v14, v73, v14
	v_cvt_pk_bf16_f32 v146, v68, v69
	v_cvt_pk_bf16_f32 v147, v70, v71
	ds_read_b64_tr_b16 v[68:69], v0 offset:27648
	ds_read_b64_tr_b16 v[70:71], v0 offset:28160
	s_waitcnt lgkmcnt(14)
	v_mfma_f32_32x32x16_bf16 v[112:127], v[164:167], v[128:131], v[112:127]
	v_add_f32_e32 v14, v74, v14
	v_add_f32_e32 v14, v75, v14
	v_add_f32_e32 v14, v76, v14
	v_add_f32_e32 v14, v77, v14
	v_cvt_pk_bf16_f32 v140, v72, v73
	v_cvt_pk_bf16_f32 v141, v74, v75
	ds_read_b64_tr_b16 v[72:73], v0 offset:31744
	ds_read_b64_tr_b16 v[74:75], v0 offset:32256
	v_mfma_f32_32x32x16_bf16 v[96:111], v[160:163], v[128:131], v[96:111]
	v_add_f32_e32 v0, v78, v14
	v_add_f32_e32 v0, v79, v0
	v_add_f32_e32 v0, 0, v0
	v_cvt_pk_bf16_f32 v142, v76, v77
	v_cvt_pk_bf16_f32 v143, v78, v79
	v_max_f32_e32 v14, v112, v113
	s_nop 5
	v_max3_f32 v15, v114, v115, v97
	v_max3_f32 v14, v14, v96, v98
	v_max3_f32 v14, v14, v99, v116
	v_max3_f32 v15, v15, v118, v119
	v_max3_f32 v14, v14, v117, v100
	v_max3_f32 v15, v15, v102, v103
	v_max3_f32 v14, v14, v101, v120
	v_max3_f32 v15, v15, v122, v123
	v_max3_f32 v14, v14, v121, v104
	v_max3_f32 v15, v15, v106, v107
	v_max3_f32 v14, v14, v105, v124
	v_max3_f32 v15, v15, v126, v127
	v_max3_f32 v76, v14, v125, v108
	v_max3_f32 v15, v15, v110, v111
	s_add_u32 s20, s18, 0xffe38000
	v_add_f32_e32 v14, v232, v0
	v_max3_f32 v0, v76, v109, v15
	s_addc_u32 s21, s19, -1
	s_add_i32 s1, s24, s27
	v_mov_b32_e32 v15, v0
	s_mov_b32 s22, m0
	s_mov_b32 m0, s1
	s_nop 0
	global_load_lds_dwordx4 v227, s[20:21]
	s_mov_b32 m0, s22
	s_add_u32 s20, s16, 0xffe38000
	s_nop 0
	v_permlane32_swap_b32_e32 v0, v15
	s_addc_u32 s21, s17, -1
	s_add_i32 s1, s2, s30
	s_mov_b32 s22, m0
	s_mov_b32 m0, s1
	s_nop 0
	global_load_lds_dwordx4 v228, s[20:21]
	s_mov_b32 m0, s22
	v_max_f32_e32 v0, v0, v15
	s_mov_b32 s1, 0x41000000
	v_cmp_lt_f32_e32 vcc, s1, v0
	s_cmp_lg_u64 vcc, 0
	s_cselect_b64 s[20:21], -1, 0
	s_cbranch_vccnz .LBB0_791

.LBB0_786:
	s_add_i32 s1, s2, 0x2000
	s_cmpk_lg_i32 s2, 0x4000
	s_cselect_b32 s34, s1, 0
	v_add_u32_e32 v15, s24, v230
	ds_read_b64_tr_b16 v[160:161], v15 offset:24576
	ds_read_b64_tr_b16 v[162:163], v15 offset:25088
	s_waitcnt lgkmcnt(9)
	v_mfma_f32_32x32x16_bf16 v[80:95], v[76:79], v[148:151], v[48:63]
	v_add_f32_e32 v2, v112, v113
	v_add_f32_e32 v2, v114, v2
	v_add_f32_e32 v2, v115, v2
	v_add_f32_e32 v2, v116, v2
	v_add_f32_e32 v2, v117, v2
	v_cvt_pk_bf16_f32 v156, v112, v113
	v_cvt_pk_bf16_f32 v157, v114, v115
	ds_read_b64_tr_b16 v[112:113], v15 offset:28672
	ds_read_b64_tr_b16 v[114:115], v15 offset:29184
	s_waitcnt lgkmcnt(10)
	v_mfma_f32_32x32x16_bf16 v[64:79], v[184:187], v[148:151], v[48:63]
	v_add_f32_e32 v2, v118, v2
	v_add_f32_e32 v2, v119, v2
	v_add_f32_e32 v2, v120, v2
	v_add_f32_e32 v6, v121, v2
	v_cvt_pk_bf16_f32 v158, v116, v117
	v_cvt_pk_bf16_f32 v159, v118, v119
	ds_read_b64_tr_b16 v[2:3], v15 offset:25600
	ds_read_b64_tr_b16 v[4:5], v15 offset:26112
	s_waitcnt lgkmcnt(11)
	v_mfma_f32_32x32x16_bf16 v[80:95], v[188:191], v[136:139], v[80:95]
	v_add_f32_e32 v6, v122, v6
	v_add_f32_e32 v6, v123, v6
	v_add_f32_e32 v6, v124, v6
	v_add_f32_e32 v10, v125, v6
	v_cvt_pk_bf16_f32 v152, v120, v121
	v_cvt_pk_bf16_f32 v153, v122, v123
	ds_read_b64_tr_b16 v[6:7], v15 offset:29696
	ds_read_b64_tr_b16 v[8:9], v15 offset:30208
	s_waitcnt lgkmcnt(12)
	v_mfma_f32_32x32x16_bf16 v[64:79], v[180:183], v[136:139], v[64:79]
	v_add_f32_e32 v10, v126, v10
	v_add_f32_e32 v10, v127, v10
	v_add_f32_e32 v10, v96, v10
	v_add_f32_e32 v116, v97, v10
	v_cvt_pk_bf16_f32 v154, v124, v125
	v_cvt_pk_bf16_f32 v155, v126, v127
	ds_read_b64_tr_b16 v[10:11], v15 offset:26624
	ds_read_b64_tr_b16 v[12:13], v15 offset:27136
	s_waitcnt lgkmcnt(13)
	v_mfma_f32_32x32x16_bf16 v[80:95], v[176:179], v[132:135], v[80:95]
	v_add_f32_e32 v116, v98, v116
	v_add_f32_e32 v116, v99, v116
	v_add_f32_e32 v116, v100, v116
	v_add_f32_e32 v116, v101, v116
	v_cvt_pk_bf16_f32 v144, v96, v97
	v_cvt_pk_bf16_f32 v145, v98, v99
	ds_read_b64_tr_b16 v[96:97], v15 offset:30720
	ds_read_b64_tr_b16 v[98:99], v15 offset:31232
	s_waitcnt lgkmcnt(14)
	v_mfma_f32_32x32x16_bf16 v[64:79], v[172:175], v[132:135], v[64:79]
	v_add_f32_e32 v116, v102, v116
	v_add_f32_e32 v116, v103, v116
	v_add_f32_e32 v116, v104, v116
	v_add_f32_e32 v116, v105, v116
	v_cvt_pk_bf16_f32 v146, v100, v101
	v_cvt_pk_bf16_f32 v147, v102, v103
	ds_read_b64_tr_b16 v[100:101], v15 offset:27648
	ds_read_b64_tr_b16 v[102:103], v15 offset:28160
	s_waitcnt lgkmcnt(14)
	v_mfma_f32_32x32x16_bf16 v[80:95], v[168:171], v[128:131], v[80:95]
	v_add_f32_e32 v116, v106, v116
	v_add_f32_e32 v116, v107, v116
	v_add_f32_e32 v116, v108, v116
	v_add_f32_e32 v116, v109, v116
	v_cvt_pk_bf16_f32 v140, v104, v105
	v_cvt_pk_bf16_f32 v141, v106, v107
	ds_read_b64_tr_b16 v[104:105], v15 offset:31744
	ds_read_b64_tr_b16 v[106:107], v15 offset:32256
	v_mfma_f32_32x32x16_bf16 v[64:79], v[164:167], v[128:131], v[64:79]
	v_add_f32_e32 v15, v110, v116
	v_add_f32_e32 v15, v111, v15
	v_add_f32_e32 v15, 0, v15
	v_cvt_pk_bf16_f32 v142, v108, v109
	v_cvt_pk_bf16_f32 v143, v110, v111
	v_max_f32_e32 v108, v80, v81
	s_nop 5
	v_max3_f32 v109, v82, v83, v65
	v_max3_f32 v108, v108, v64, v66
	v_max3_f32 v108, v108, v67, v84
	v_max3_f32 v109, v109, v86, v87
	v_max3_f32 v108, v108, v85, v68
	v_max3_f32 v109, v109, v70, v71
	v_max3_f32 v108, v108, v69, v88
	v_max3_f32 v109, v109, v90, v91
	v_max3_f32 v108, v108, v89, v72
	v_max3_f32 v109, v109, v74, v75
	v_max3_f32 v108, v108, v73, v92
	v_max3_f32 v109, v109, v94, v95
	v_max3_f32 v108, v108, v93, v76
	v_max3_f32 v109, v109, v78, v79
	v_add_f32_e32 v232, v14, v15
	v_max3_f32 v14, v108, v77, v109
	v_mov_b32_e32 v15, v14
	s_add_i32 s1, s2, s27
	s_nop 0
	v_permlane32_swap_b32_e32 v14, v15
	s_mov_b32 s20, m0
	s_mov_b32 m0, s1
	s_nop 0
	global_load_lds_dwordx4 v227, s[18:19]
	s_mov_b32 m0, s20
	s_add_i32 s1, s34, s30
	s_mov_b32 s20, m0
	s_mov_b32 m0, s1
	s_nop 0
	global_load_lds_dwordx4 v228, s[16:17]
	s_mov_b32 m0, s20
	v_max_f32_e32 v14, v14, v15
	s_mov_b32 s1, 0x41000000
	v_cmp_lt_f32_e32 vcc, s1, v14
	s_cmp_lg_u64 vcc, 0
	s_cselect_b64 s[20:21], -1, 0
	s_cbranch_vccnz .LBB0_794

.LBB0_2404:
	v_add_u32_e32 v0, s20, v231
	ds_read_b64_tr_b16 v[192:193], v0 offset:24576
	ds_read_b64_tr_b16 v[194:195], v0 offset:25088
	s_waitcnt lgkmcnt(9)
	v_mfma_f32_32x32x16_bf16 v[112:127], v[188:191], v[148:151], v[48:63]
	v_add_f32_e32 v2, v80, v81
	v_add_f32_e32 v2, v82, v2
	v_add_f32_e32 v2, v83, v2
	v_add_f32_e32 v2, v84, v2
	v_add_f32_e32 v2, v85, v2
	v_cvt_pk_bf16_f32 v156, v80, v81
	v_cvt_pk_bf16_f32 v157, v82, v83
	ds_read_b64_tr_b16 v[80:81], v0 offset:28672
	ds_read_b64_tr_b16 v[82:83], v0 offset:29184
	s_waitcnt lgkmcnt(10)
	v_mfma_f32_32x32x16_bf16 v[96:111], v[184:187], v[148:151], v[48:63]
	v_add_f32_e32 v2, v86, v2
	v_add_f32_e32 v2, v87, v2
	v_add_f32_e32 v2, v88, v2
	v_add_f32_e32 v6, v89, v2
	v_cvt_pk_bf16_f32 v158, v84, v85
	v_cvt_pk_bf16_f32 v159, v86, v87
	ds_read_b64_tr_b16 v[2:3], v0 offset:25600
	ds_read_b64_tr_b16 v[4:5], v0 offset:26112
	s_waitcnt lgkmcnt(11)
	v_mfma_f32_32x32x16_bf16 v[112:127], v[180:183], v[136:139], v[112:127]
	v_add_f32_e32 v6, v90, v6
	v_add_f32_e32 v6, v91, v6
	v_add_f32_e32 v6, v92, v6
	v_add_f32_e32 v10, v93, v6
	v_cvt_pk_bf16_f32 v152, v88, v89
	v_cvt_pk_bf16_f32 v153, v90, v91
	ds_read_b64_tr_b16 v[6:7], v0 offset:29696
	ds_read_b64_tr_b16 v[8:9], v0 offset:30208
	s_waitcnt lgkmcnt(12)
	v_mfma_f32_32x32x16_bf16 v[96:111], v[176:179], v[136:139], v[96:111]
	v_add_f32_e32 v10, v94, v10
	v_add_f32_e32 v10, v95, v10
	v_add_f32_e32 v10, v64, v10
	v_add_f32_e32 v14, v65, v10
	v_cvt_pk_bf16_f32 v154, v92, v93
	v_cvt_pk_bf16_f32 v155, v94, v95
	ds_read_b64_tr_b16 v[10:11], v0 offset:26624
	ds_read_b64_tr_b16 v[12:13], v0 offset:27136
	s_waitcnt lgkmcnt(13)
	v_mfma_f32_32x32x16_bf16 v[112:127], v[172:175], v[132:135], v[112:127]
	v_add_f32_e32 v14, v66, v14
	v_add_f32_e32 v14, v67, v14
	v_add_f32_e32 v14, v68, v14
	v_add_f32_e32 v14, v69, v14
	v_cvt_pk_bf16_f32 v144, v64, v65
	v_cvt_pk_bf16_f32 v145, v66, v67
	ds_read_b64_tr_b16 v[64:65], v0 offset:30720
	ds_read_b64_tr_b16 v[66:67], v0 offset:31232
	s_waitcnt lgkmcnt(14)
	v_mfma_f32_32x32x16_bf16 v[96:111], v[168:171], v[132:135], v[96:111]
	v_add_f32_e32 v14, v70, v14
	v_add_f32_e32 v14, v71, v14
	v_add_f32_e32 v14, v72, v14
	v_add_f32_e32 v14, v73, v14
	v_cvt_pk_bf16_f32 v146, v68, v69
	v_cvt_pk_bf16_f32 v147, v70, v71
	ds_read_b64_tr_b16 v[68:69], v0 offset:27648
	ds_read_b64_tr_b16 v[70:71], v0 offset:28160
	s_waitcnt lgkmcnt(14)
	v_mfma_f32_32x32x16_bf16 v[112:127], v[164:167], v[128:131], v[112:127]
	v_add_f32_e32 v14, v74, v14
	v_add_f32_e32 v14, v75, v14
	v_add_f32_e32 v14, v76, v14
	v_add_f32_e32 v14, v77, v14
	v_cvt_pk_bf16_f32 v140, v72, v73
	v_cvt_pk_bf16_f32 v141, v74, v75
	ds_read_b64_tr_b16 v[72:73], v0 offset:31744
	ds_read_b64_tr_b16 v[74:75], v0 offset:32256
	v_mfma_f32_32x32x16_bf16 v[96:111], v[160:163], v[128:131], v[96:111]
	v_add_f32_e32 v0, v78, v14
	v_add_f32_e32 v0, v79, v0
	v_add_f32_e32 v0, 0, v0
	v_cvt_pk_bf16_f32 v142, v76, v77
	v_cvt_pk_bf16_f32 v143, v78, v79
	v_max_f32_e32 v14, v112, v113
	s_nop 5
	v_max3_f32 v15, v114, v115, v97
	v_max3_f32 v14, v14, v96, v98
	v_max3_f32 v14, v14, v99, v116
	v_max3_f32 v15, v15, v118, v119
	v_max3_f32 v14, v14, v117, v100
	v_max3_f32 v15, v15, v102, v103
	v_max3_f32 v14, v14, v101, v120
	v_max3_f32 v15, v15, v122, v123
	v_max3_f32 v14, v14, v121, v104
	v_max3_f32 v15, v15, v106, v107
	v_max3_f32 v14, v14, v105, v124
	v_max3_f32 v15, v15, v126, v127
	v_max3_f32 v76, v14, v125, v108
	v_max3_f32 v15, v15, v110, v111
	v_add_f32_e32 v14, v233, v0
	v_max3_f32 v0, v76, v109, v15
	v_mov_b32_e32 v15, v0
	s_add_u32 s20, s18, 0xffe38000
	s_nop 0
	v_permlane32_swap_b32_e32 v0, v15
	s_addc_u32 s21, s19, -1
	s_add_i32 s0, s24, s27
	s_mov_b32 s22, m0
	s_mov_b32 m0, s0
	s_nop 0
	global_load_lds_dwordx4 v228, s[20:21]
	s_mov_b32 m0, s22
	s_add_u32 s20, s16, 0xffe38000
	v_max_f32_e32 v0, v0, v15
	s_addc_u32 s21, s17, -1
	s_add_i32 s0, s2, s30
	s_mov_b32 s22, m0
	s_mov_b32 m0, s0
	s_nop 0
	global_load_lds_dwordx4 v229, s[20:21]
	s_mov_b32 m0, s22
	v_cmp_lt_f32_e32 vcc, s49, v0
	s_cmp_lg_u64 vcc, 0
	s_cselect_b64 s[20:21], -1, 0
	s_cbranch_vccnz .LBB0_2412

.LBB0_2407:
	s_add_i32 s0, s2, 0x2000
	s_cmpk_lg_i32 s2, 0x4000
	s_cselect_b32 s34, s0, 0
	v_add_u32_e32 v15, s24, v231
	ds_read_b64_tr_b16 v[160:161], v15 offset:24576
	ds_read_b64_tr_b16 v[162:163], v15 offset:25088
	s_waitcnt lgkmcnt(9)
	v_mfma_f32_32x32x16_bf16 v[80:95], v[76:79], v[148:151], v[48:63]
	v_add_f32_e32 v2, v112, v113
	v_add_f32_e32 v2, v114, v2
	v_add_f32_e32 v2, v115, v2
	v_add_f32_e32 v2, v116, v2
	v_add_f32_e32 v2, v117, v2
	v_cvt_pk_bf16_f32 v156, v112, v113
	v_cvt_pk_bf16_f32 v157, v114, v115
	ds_read_b64_tr_b16 v[112:113], v15 offset:28672
	ds_read_b64_tr_b16 v[114:115], v15 offset:29184
	s_waitcnt lgkmcnt(10)
	v_mfma_f32_32x32x16_bf16 v[64:79], v[184:187], v[148:151], v[48:63]
	v_add_f32_e32 v2, v118, v2
	v_add_f32_e32 v2, v119, v2
	v_add_f32_e32 v2, v120, v2
	v_add_f32_e32 v6, v121, v2
	v_cvt_pk_bf16_f32 v158, v116, v117
	v_cvt_pk_bf16_f32 v159, v118, v119
	ds_read_b64_tr_b16 v[2:3], v15 offset:25600
	ds_read_b64_tr_b16 v[4:5], v15 offset:26112
	s_waitcnt lgkmcnt(11)
	v_mfma_f32_32x32x16_bf16 v[80:95], v[188:191], v[136:139], v[80:95]
	v_add_f32_e32 v6, v122, v6
	v_add_f32_e32 v6, v123, v6
	v_add_f32_e32 v6, v124, v6
	v_add_f32_e32 v10, v125, v6
	v_cvt_pk_bf16_f32 v152, v120, v121
	v_cvt_pk_bf16_f32 v153, v122, v123
	ds_read_b64_tr_b16 v[6:7], v15 offset:29696
	ds_read_b64_tr_b16 v[8:9], v15 offset:30208
	s_waitcnt lgkmcnt(12)
	v_mfma_f32_32x32x16_bf16 v[64:79], v[180:183], v[136:139], v[64:79]
	v_add_f32_e32 v10, v126, v10
	v_add_f32_e32 v10, v127, v10
	v_add_f32_e32 v10, v96, v10
	v_add_f32_e32 v116, v97, v10
	v_cvt_pk_bf16_f32 v154, v124, v125
	v_cvt_pk_bf16_f32 v155, v126, v127
	ds_read_b64_tr_b16 v[10:11], v15 offset:26624
	ds_read_b64_tr_b16 v[12:13], v15 offset:27136
	s_waitcnt lgkmcnt(13)
	v_mfma_f32_32x32x16_bf16 v[80:95], v[176:179], v[132:135], v[80:95]
	v_add_f32_e32 v116, v98, v116
	v_add_f32_e32 v116, v99, v116
	v_add_f32_e32 v116, v100, v116
	v_add_f32_e32 v116, v101, v116
	v_cvt_pk_bf16_f32 v144, v96, v97
	v_cvt_pk_bf16_f32 v145, v98, v99
	ds_read_b64_tr_b16 v[96:97], v15 offset:30720
	ds_read_b64_tr_b16 v[98:99], v15 offset:31232
	s_waitcnt lgkmcnt(14)
	v_mfma_f32_32x32x16_bf16 v[64:79], v[172:175], v[132:135], v[64:79]
	v_add_f32_e32 v116, v102, v116
	v_add_f32_e32 v116, v103, v116
	v_add_f32_e32 v116, v104, v116
	v_add_f32_e32 v116, v105, v116
	v_cvt_pk_bf16_f32 v146, v100, v101
	v_cvt_pk_bf16_f32 v147, v102, v103
	ds_read_b64_tr_b16 v[100:101], v15 offset:27648
	ds_read_b64_tr_b16 v[102:103], v15 offset:28160
	s_waitcnt lgkmcnt(14)
	v_mfma_f32_32x32x16_bf16 v[80:95], v[168:171], v[128:131], v[80:95]
	v_add_f32_e32 v116, v106, v116
	v_add_f32_e32 v116, v107, v116
	v_add_f32_e32 v116, v108, v116
	v_add_f32_e32 v116, v109, v116
	v_cvt_pk_bf16_f32 v140, v104, v105
	v_cvt_pk_bf16_f32 v141, v106, v107
	ds_read_b64_tr_b16 v[104:105], v15 offset:31744
	ds_read_b64_tr_b16 v[106:107], v15 offset:32256
	v_mfma_f32_32x32x16_bf16 v[64:79], v[164:167], v[128:131], v[64:79]
	v_add_f32_e32 v15, v110, v116
	v_add_f32_e32 v15, v111, v15
	v_add_f32_e32 v15, 0, v15
	v_cvt_pk_bf16_f32 v142, v108, v109
	v_cvt_pk_bf16_f32 v143, v110, v111
	v_max_f32_e32 v108, v80, v81
	s_nop 5
	v_max3_f32 v109, v82, v83, v65
	v_max3_f32 v108, v108, v64, v66
	v_max3_f32 v108, v108, v67, v84
	v_max3_f32 v109, v109, v86, v87
	v_max3_f32 v108, v108, v85, v68
	v_max3_f32 v109, v109, v70, v71
	v_max3_f32 v108, v108, v69, v88
	v_max3_f32 v109, v109, v90, v91
	v_max3_f32 v108, v108, v89, v72
	v_max3_f32 v109, v109, v74, v75
	v_max3_f32 v108, v108, v73, v92
	v_max3_f32 v109, v109, v94, v95
	v_max3_f32 v108, v108, v93, v76
	v_max3_f32 v109, v109, v78, v79
	v_add_f32_e32 v233, v14, v15
	v_max3_f32 v14, v108, v77, v109
	v_mov_b32_e32 v15, v14
	s_nop 1
	v_permlane32_swap_b32_e32 v14, v15
	s_add_i32 s0, s2, s27
	s_mov_b32 s20, m0
	s_mov_b32 m0, s0
	s_nop 0
	global_load_lds_dwordx4 v228, s[18:19]
	s_mov_b32 m0, s20
	v_max_f32_e32 v14, v14, v15
	s_add_i32 s0, s34, s30
	s_mov_b32 s20, m0
	s_mov_b32 m0, s0
	s_nop 0
	global_load_lds_dwordx4 v229, s[16:17]
	s_mov_b32 m0, s20
	v_cmp_lt_f32_e32 vcc, s49, v14
	s_cmp_lg_u64 vcc, 0
	s_cselect_b64 s[20:21], -1, 0
	s_cbranch_vccnz .LBB0_2415
